# same as the previous version with the own/partner queue-state lane writes moved two instructions behind the v_readfirstlane that produce them (VALU-SGPR wait states)
# baseline (speedup 1.0000x reference)
.LBB0_1621:
	s_waitcnt lgkmcnt(0)
	s_add_u32 s14, s8, 0x3fa00000
	s_addc_u32 s15, s9, 0
	s_waitcnt lgkmcnt(0)
	s_barrier
	s_cmp_gt_i32 s40, 0
	v_and_b32_e32 v38, 15, v173
	s_cselect_b64 s[20:21], -1, 0
	s_cmp_lt_i32 s40, 1
	v_lshlrev_b32_e32 v40, 2, v43
	s_cbranch_scc1 .LBB0_1658
	s_lshl_b64 s[22:23], s[90:91], 11
	s_lshl_b64 s[24:25], s[90:91], 6
	s_add_i32 s3, 0, 0x1c000
	s_add_i32 s52, 0, 0x18000
	s_add_i32 s41, s40, -1
	s_add_u32 s42, s8, 0x33400000
	s_addc_u32 s43, s9, 0
	v_lshrrev_b32_e32 v0, 4, v2
	s_add_u32 s44, s8, 0x586c0000
	v_lshl_or_b32 v58, s2, 2, v0
	s_addc_u32 s45, s9, 0
	v_lshlrev_b32_e32 v0, 4, v58
	v_and_b32_e32 v2, 12, v38
	s_add_u32 s46, s8, 0x4c6c0000
	v_add3_u32 v59, s3, v0, v2
	v_lshlrev_b32_e32 v0, 8, v58
	v_lshlrev_b32_e32 v2, 4, v38
	s_addc_u32 s48, s9, 0
	s_lshl_b32 s2, s2, 10
	v_add3_u32 v60, s52, v0, v2
	s_add_i32 s49, s2, 0
	s_add_i32 s52, s52, s2
	v_readlane_b32 s2, v253, 53
	v_mov_b32_e32 v41, v1
	v_lshl_add_u32 v61, v43, 4, s3
	s_mul_i32 s2, s2, s38
	v_readlane_b32 s3, v253, 52
	v_lshlrev_b32_e32 v0, 6, v58
	v_lshl_add_u64 v[44:45], s[14:15], 0, v[40:41]
	v_lshrrev_b32_e32 v41, 4, v43
	s_sub_i32 s54, s3, s2
	s_not_b32 s2, s38
	v_readlane_b32 s3, v253, 2
	v_lshlrev_b32_e32 v42, 2, v38
	v_lshlrev_b32_e32 v46, 12, v41
	v_mov_b32_e32 v47, v1
	s_mul_i32 s55, s3, s2
	v_mov_b32_e32 v2, v1
	v_mov_b32_e32 v3, v1
	v_mov_b32_e32 v4, v1
	v_mov_b32_e32 v5, v1
	s_mov_b32 s57, 0
	s_movk_i32 s58, 0xf000
	s_movk_i32 s59, 0xc000
	v_lshlrev_b32_e32 v48, 2, v0
	v_lshlrev_b32_e32 v0, 2, v40
	v_lshlrev_b32_e32 v50, 2, v38
	v_readlane_b32 s60, v253, 3
	s_load_dwordx2 s[64:65], s[0:1], 0x1a8
	s_load_dwordx2 s[70:71], s[0:1], 0x10
	s_waitcnt lgkmcnt(0)
	s_add_i32 s98, s47, 0x20180
	v_mov_b32_e32 v111, s98
	ds_read_b64 v[112:113], v111
	v_and_b32_e32 v114, 7, v173
	v_bfe_u32 v115, v173, 3, 3
	v_mul_u32_u24_e32 v106, 0x2c000, v115
	v_lshl_add_u32 v106, v114, 4, v106
	v_lshlrev_b32_e32 v107, 16, v115
	v_lshl_add_u32 v107, v114, 4, v107
	v_lshlrev_b32_e32 v108, 14, v114
	v_lshl_add_u32 v108, v115, 4, v108
	v_mul_u32_u24_e32 v109, 0xb000, v114
	v_lshl_add_u32 v109, v115, 4, v109
	v_lshlrev_b32_e32 v110, 5, v115
	s_add_i32 s99, s98, -32
	v_mov_b32_e32 v120, s99
	ds_read_b64 v[118:119], v120
	s_mov_b32 s94, 0
	s_mov_b32 s95, 0
	s_waitcnt lgkmcnt(0)
	v_readfirstlane_b32 s2, v112
	v_readfirstlane_b32 s3, v113
	v_readfirstlane_b32 s92, v118
	v_readfirstlane_b32 s93, v119
	s_mov_b32 s4, 1
	v_writelane_b32 v117, s2, 0
	v_writelane_b32 v117, s3, 1
	v_writelane_b32 v117, s4, 2
	s_branch .LBB0_1625
